# GEMM K-loop heads aligned to 64 bytes on top of previous
# baseline (speedup 1.0000x reference)
; #define PG8_STAGE(bufoff, gbase, voff) do { _Pragma("unroll") for (int _i = 0; _i < 2; ++_i) \
;         __builtin_amdgcn_global_load_lds((const unsigned*)((const char*)(gbase) + (voff)[_i]), (LAS unsigned*)(lds + (bufoff) + ldsw + _i * 8192), 16, 0, 0); } while (0)
; #define PG8_LDA(dst, b, h) do { _Pragma("unroll") for (int m = 0; m < 4; ++m) _Pragma("unroll") for (int k = 0; k < 2; ++k) dst[m][k] = *(const LAS bf16x8*)(lds + PG8_SA(b, h) + aoff + m * 2048 + k * 1024); } while (0)
; #define PG8_LDB(dst, b, h) do { _Pragma("unroll") for (int n = 0; n < 2; ++n) _Pragma("unroll") for (int k = 0; k < 2; ++k) dst[n][k] = *(const LAS bf16x8*)(lds + PG8_SB(b, h) + boff + n * 2048 + k * 1024); } while (0)
; #define PG8_SCHED __builtin_amdgcn_sched_barrier(0)
; template <class Epi, bool ALIGN_EPI>
; __device__ __forceinline__ void gemm_phase(LAS unsigned char* lds, const Gemm g, const StaticOrder& S, const Epi& E, const int tid) {
;     ...
;         const bool has_next = S.next(ui + 1, nxt);
;         const char* nA = has_next ? (const char*)g.A + (size_t)nxt.pm * tstepA + (size_t)nxt.pn * g.acs : cA; const char* nB = has_next ? (const char*)g.Bt + (size_t)nxt.pn * tstepB : cB;
;         for (int t = 0; t < nt; t += 2) {
;             const bool last = (t == nt - 2);
;             const char* a1 = cA + (size_t)(t + 1) * kstepA;
;             const char* a2 = last ? nA : cA + (size_t)(t + 2) * kstepA; const char* b2 = last ? nB : cB + (size_t)(t + 2) * kstepB;
;             const char* a3 = a2 + kstepA; const char* b3 = b2 + kstepB;
;             PG8_LDB(B0, 0, 0); PG8_LDB(B1, 0, 1); PG8_SCHED; PG8_LDA(At, 0, 0); PG8_STAGE(PG8_SA(1, 1), a1 + hstepA, voffA);
.LBB0_210:
	s_ashr_i32 s43, s42, 31
	s_lshl_b64 s[44:45], s[42:43], 20
	s_add_u32 s44, s56, s44
	s_addc_u32 s45, s57, s45
	s_and_b64 s[46:47], s[40:41], exec
	s_cselect_b32 s43, s45, s49
	s_cselect_b32 s87, s44, s48
	s_ashr_i32 s35, s34, 31
	s_lshl_b64 s[46:47], s[34:35], 20
	s_add_u32 s46, s60, s46
	s_addc_u32 s47, s61, s47
	s_and_b64 s[52:53], s[40:41], exec
	s_cselect_b32 s35, s47, s51
	s_cselect_b32 vcc_lo, s46, s50
	s_add_u32 s48, s48, 0xc000
	s_addc_u32 s49, s49, 0
	s_add_u32 vcc_hi, s50, 0x10000
	s_addc_u32 s88, s51, 0
	s_mov_b32 s89, -2
	.p2align 6

; #define PG8_STAGE(bufoff, gbase, voff) do { _Pragma("unroll") for (int _i = 0; _i < 2; ++_i) \
;         __builtin_amdgcn_global_load_lds((const unsigned*)((const char*)(gbase) + (voff)[_i]), (LAS unsigned*)(lds + (bufoff) + ldsw + _i * 8192), 16, 0, 0); } while (0)
; #define PG8_LDA(dst, b, h) do { _Pragma("unroll") for (int m = 0; m < 4; ++m) _Pragma("unroll") for (int k = 0; k < 2; ++k) dst[m][k] = *(const LAS bf16x8*)(lds + PG8_SA(b, h) + aoff + m * 2048 + k * 1024); } while (0)
; #define PG8_LDB(dst, b, h) do { _Pragma("unroll") for (int n = 0; n < 2; ++n) _Pragma("unroll") for (int k = 0; k < 2; ++k) dst[n][k] = *(const LAS bf16x8*)(lds + PG8_SB(b, h) + boff + n * 2048 + k * 1024); } while (0)
; #define PG8_SCHED __builtin_amdgcn_sched_barrier(0)
; template <class Epi, bool ALIGN_EPI>
; __device__ __forceinline__ void gemm_phase(LAS unsigned char* lds, const Gemm g, const StaticOrder& S, const Epi& E, const int tid) {
;     ...
;         const bool has_next = S.next(ui + 1, nxt);
;         const char* nA = has_next ? (const char*)g.A + (size_t)nxt.pm * tstepA + (size_t)nxt.pn * g.acs : cA; const char* nB = has_next ? (const char*)g.Bt + (size_t)nxt.pn * tstepB : cB;
;         for (int t = 0; t < nt; t += 2) {
;             const bool last = (t == nt - 2);
;             const char* a1 = cA + (size_t)(t + 1) * kstepA;
;             const char* a2 = last ? nA : cA + (size_t)(t + 2) * kstepA; const char* b2 = last ? nB : cB + (size_t)(t + 2) * kstepB;
;             const char* a3 = a2 + kstepA; const char* b3 = b2 + kstepB;
;             PG8_LDB(B0, 0, 0); PG8_LDB(B1, 0, 1); PG8_SCHED; PG8_LDA(At, 0, 0); PG8_STAGE(PG8_SA(1, 1), a1 + hstepA, voffA);
.LBB0_293:
	s_add_u32 s84, s10, 0x10000
	s_addc_u32 s85, s11, 0
	s_add_u32 s10, s22, 0xc000
	s_addc_u32 s11, s23, 0
	s_mov_b32 s86, -2
	.p2align 6

; #define PG8_STAGE(bufoff, gbase, voff) do { _Pragma("unroll") for (int _i = 0; _i < 2; ++_i) \
;         __builtin_amdgcn_global_load_lds((const unsigned*)((const char*)(gbase) + (voff)[_i]), (LAS unsigned*)(lds + (bufoff) + ldsw + _i * 8192), 16, 0, 0); } while (0)
; #define PG8_LDA(dst, b, h) do { _Pragma("unroll") for (int m = 0; m < 4; ++m) _Pragma("unroll") for (int k = 0; k < 2; ++k) dst[m][k] = *(const LAS bf16x8*)(lds + PG8_SA(b, h) + aoff + m * 2048 + k * 1024); } while (0)
; #define PG8_LDB(dst, b, h) do { _Pragma("unroll") for (int n = 0; n < 2; ++n) _Pragma("unroll") for (int k = 0; k < 2; ++k) dst[n][k] = *(const LAS bf16x8*)(lds + PG8_SB(b, h) + boff + n * 2048 + k * 1024); } while (0)
; #define PG8_SCHED __builtin_amdgcn_sched_barrier(0)
; template <class Epi, bool ALIGN_EPI>
; __device__ __forceinline__ void gemm_phase(LAS unsigned char* lds, const Gemm g, const StaticOrder& S, const Epi& E, const int tid) {
;     ...
;         const bool has_next = S.next(ui + 1, nxt);
;         const char* nA = has_next ? (const char*)g.A + (size_t)nxt.pm * tstepA + (size_t)nxt.pn * g.acs : cA; const char* nB = has_next ? (const char*)g.Bt + (size_t)nxt.pn * tstepB : cB;
;         for (int t = 0; t < nt; t += 2) {
;             const bool last = (t == nt - 2);
;             const char* a1 = cA + (size_t)(t + 1) * kstepA;
;             const char* a2 = last ? nA : cA + (size_t)(t + 2) * kstepA; const char* b2 = last ? nB : cB + (size_t)(t + 2) * kstepB;
;             const char* a3 = a2 + kstepA; const char* b3 = b2 + kstepB;
;             PG8_LDB(B0, 0, 0); PG8_LDB(B1, 0, 1); PG8_SCHED; PG8_LDA(At, 0, 0); PG8_STAGE(PG8_SA(1, 1), a1 + hstepA, voffA);
.LBB0_384:
	s_ashr_i32 s43, s42, 31
	s_lshl_b64 s[44:45], s[42:43], 20
	s_add_u32 s44, s30, s44
	s_addc_u32 s45, s56, s45
	s_and_b64 s[46:47], s[38:39], exec
	s_cselect_b32 s43, s45, s49
	s_cselect_b32 s84, s44, s48
	s_ashr_i32 s41, s40, 31
	s_lshl_b64 s[46:47], s[40:41], 20
	s_add_u32 s46, s57, s46
	s_addc_u32 s47, s60, s47
	s_and_b64 s[52:53], s[38:39], exec
	s_cselect_b32 s41, s47, s51
	s_cselect_b32 s85, s46, s50
	s_add_u32 s48, s48, 0xc000
	s_addc_u32 s49, s49, 0
	s_add_u32 s86, s50, 0x10000
	s_addc_u32 s87, s51, 0
	s_mov_b32 s88, -2
	.p2align 6

; #define PG8_STAGE(bufoff, gbase, voff) do { _Pragma("unroll") for (int _i = 0; _i < 2; ++_i) \
;         __builtin_amdgcn_global_load_lds((const unsigned*)((const char*)(gbase) + (voff)[_i]), (LAS unsigned*)(lds + (bufoff) + ldsw + _i * 8192), 16, 0, 0); } while (0)
; #define PG8_LDA(dst, b, h) do { _Pragma("unroll") for (int m = 0; m < 4; ++m) _Pragma("unroll") for (int k = 0; k < 2; ++k) dst[m][k] = *(const LAS bf16x8*)(lds + PG8_SA(b, h) + aoff + m * 2048 + k * 1024); } while (0)
; #define PG8_LDB(dst, b, h) do { _Pragma("unroll") for (int n = 0; n < 2; ++n) _Pragma("unroll") for (int k = 0; k < 2; ++k) dst[n][k] = *(const LAS bf16x8*)(lds + PG8_SB(b, h) + boff + n * 2048 + k * 1024); } while (0)
; #define PG8_SCHED __builtin_amdgcn_sched_barrier(0)
; template <class Epi, bool ALIGN_EPI>
; __device__ __forceinline__ void gemm_phase(LAS unsigned char* lds, const Gemm g, const StaticOrder& S, const Epi& E, const int tid) {
;     ...
;         const bool has_next = S.next(ui + 1, nxt);
;         const char* nA = has_next ? (const char*)g.A + (size_t)nxt.pm * tstepA + (size_t)nxt.pn * g.acs : cA; const char* nB = has_next ? (const char*)g.Bt + (size_t)nxt.pn * tstepB : cB;
;         for (int t = 0; t < nt; t += 2) {
;             const bool last = (t == nt - 2);
;             const char* a1 = cA + (size_t)(t + 1) * kstepA;
;             const char* a2 = last ? nA : cA + (size_t)(t + 2) * kstepA; const char* b2 = last ? nB : cB + (size_t)(t + 2) * kstepB;
;             const char* a3 = a2 + kstepA; const char* b3 = b2 + kstepB;
;             PG8_LDB(B0, 0, 0); PG8_LDB(B1, 0, 1); PG8_SCHED; PG8_LDA(At, 0, 0); PG8_STAGE(PG8_SA(1, 1), a1 + hstepA, voffA);
.LBB0_846:
	s_ashr_i32 s49, s48, 31
	s_lshl_b64 s[34:35], s[48:49], 20
	s_add_u32 s50, s55, s34
	s_addc_u32 s51, s56, s35
	s_and_b64 s[34:35], s[38:39], exec
	s_cselect_b32 s49, s51, s11
	s_cselect_b32 s82, s50, s10
	s_ashr_i32 s47, s46, 31
	s_lshl_b64 s[34:35], s[46:47], 20
	s_add_u32 s52, s57, s34
	s_addc_u32 s53, s60, s35
	s_and_b64 s[34:35], s[38:39], exec
	s_cselect_b32 s47, s53, s23
	s_cselect_b32 s83, s52, s22
	s_add_u32 s10, s10, 0x80080
	s_addc_u32 s11, s11, 0
	s_add_u32 s84, s22, 0x10000
	s_addc_u32 s85, s23, 0
	s_mov_b32 s86, -2
	.p2align 6
